# v27b + waves 4-7 start the B1 head loop ~1.7us later (s_sleep 60) so SIMD partners do not wait on their tile loads at the same time
# baseline (speedup 1.0000x reference)
; __device__ __forceinline__ void phase_b1(const P& p, const Ctx& c, int seg) {
;     ...
;         const size_t row = (size_t)r0 + l15; const int tl = tl0 + l15;
;         const bf16_t* curp = P1 + row * P1W; const bf16_t* prevp = (tl > 0) ? (P1 + (row - 1) * P1W) : (PTr + (size_t)b * RW_SHIFT); const bool hasprev = (tl > 0) || (seg > 0);
;         struct TileIn { u32x4 cr, ck, cv, pr, pk, pv, vf; };
;         struct TilePar { f32x4 m0, m1, m2, w0, a0, v0, kkw, kaw, rk; };
; #pragma unroll 1
;         for (int x = 0; x < 3; ++x) {
;             int hh = c.wv * 3 + x; asm volatile("" : "+s"(hh));
.LBB0_732:
	s_or_b64 exec, exec, s[12:13]
	v_readlane_b32 s10, v255, 31
	s_mov_b64 s[12:13], 0x1800
	v_mov_b64_e32 v[6:7], s[96:97]
	v_or_b32_e32 v3, s10, v3
	s_mov_b32 s10, 0
	v_cmp_ne_u32_e32 vcc, 0, v3
	v_lshl_add_u64 v[156:157], v[152:153], 0, s[12:13]
	s_mov_b64 s[52:53], 0x1800
	v_lshl_add_u64 v[158:159], v[154:155], 0, s[12:13]
	v_mad_i64_i32 v[160:161], s[12:13], v2, s65, v[6:7]
	s_mul_hi_i32 s11, s34, 24
	s_mul_i32 s45, s34, 24
	v_mad_i64_i32 v[162:163], s[12:13], v2, s58, -4
	v_mad_i64_i32 v[164:165], s[12:13], v2, 24, 0
	s_cmp_lt_u32 s46, 12
	s_cbranch_scc1 .Lb1_nostag
	s_sleep 60
.Lb1_nostag:
	s_branch .LBB0_734
.LBB0_733:
	s_or_b64 exec, exec, s[12:13]
	s_add_i32 s10, s10, 1
	s_cmp_eq_u32 s10, 3
	s_cbranch_scc1 .LBB0_758
